# v47 = v43 with the de-phase sleep of the second workgroup per CU shortened 48 -> 28 in the MT2 GEMM phases (w_out, mlp2)
# speedup vs baseline: 1.0133x; 1.0133x over previous
.LBB0_827:
	s_mov_b32 s6, 1
	s_cmp_ge_i32 s56, s6
	s_mov_b64 s[8:9], -1
	s_cbranch_scc1 .LBB0_826
	s_and_b64 vcc, exec, s[2:3]
	s_cbranch_vccnz .LBB0_830
	s_sleep 28

.LBB0_1060:
	s_mov_b32 s0, 1
	s_cmp_ge_i32 s59, s0
	s_mov_b64 s[8:9], -1
	s_cbranch_scc1 .LBB0_1059
	s_and_b64 vcc, exec, s[2:3]
	s_cbranch_vccnz .LBB0_1063
	s_sleep 28

.LBB0_1807:
	s_mov_b32 s6, 1
	s_cmp_ge_i32 s55, s6
	s_mov_b64 s[8:9], -1
	s_cbranch_scc1 .LBB0_1806
	s_and_b64 vcc, exec, s[2:3]
	s_cbranch_vccnz .LBB0_1810
	s_sleep 28

.LBB0_2040:
	s_mov_b32 s0, 1
	s_cmp_ge_i32 s56, s0
	s_mov_b64 s[8:9], -1
	s_cbranch_scc1 .LBB0_2039
	s_and_b64 vcc, exec, s[2:3]
	s_cbranch_vccnz .LBB0_2043
	s_sleep 28
